# static priority raise (s_setprio 3) for the latency-critical GDN scan waves in P3a, reset before the barrier
# baseline (speedup 1.0000x reference)
.LBB0_905:
	s_andn2_b64 vcc, exec, s[0:1]
	s_cbranch_vccnz .LBB0_931
	s_setprio 3
	v_mov_b32_e32 v185, v181
	s_movk_i32 s0, 0x3c0
	v_ashrrev_i32_e32 v167, 6, v185
	v_lshlrev_b32_e32 v192, 10, v167
	v_lshlrev_b32_e32 v0, 6, v185
	v_and_or_b32 v0, v0, s0, v192
	v_lshrrev_b32_e32 v2, 1, v185
	v_ashrrev_i32_e32 v1, 31, v0
	v_and_b32_e32 v168, 24, v2
	v_lshl_add_u64 v[0:1], v[0:1], 1, s[20:21]
	s_waitcnt vmcnt(16)
	v_lshlrev_b32_e32 v160, 1, v168
	v_mov_b32_e32 v161, 0
	v_and_b32_e32 v166, 63, v185
	v_lshl_add_u64 v[0:1], v[0:1], 0, v[160:161]
	s_mov_b64 s[4:5], 0x11048000
	v_lshl_add_u64 v[176:177], v[0:1], 0, s[4:5]
	v_lshl_or_b32 v0, v166, 4, v192
	v_ashrrev_i32_e32 v1, 31, v0
	v_lshlrev_b64 v[162:163], 1, v[0:1]
	v_and_b32_e32 v206, 31, v166
	v_lshlrev_b32_e32 v206, 5, v206
	v_lshrrev_b32_e32 v207, 5, v166
	v_lshl_or_b32 v206, v207, 4, v206
	v_lshl_add_u32 v206, v192, 1, v206
	v_mov_b32_e32 v207, 0
	s_mov_b32 s1, 0
	v_lshl_add_u64 v[164:165], s[20:21], 0, v[162:163]
	s_mov_b64 s[4:5], 0x13148000
	s_lshl_b32 s0, s2, 19
	v_lshl_add_u64 v[178:179], v[164:165], 0, s[4:5]
	s_lshl_b64 s[4:5], s[0:1], 1
	v_lshl_add_u64 v[8:9], v[176:177], 0, s[4:5]
	v_lshl_add_u64 v[16:17], v[178:179], 0, s[4:5]
	s_or_b32 s4, s0, 0x1000
	s_mov_b32 s5, s1
	s_lshl_b64 s[4:5], s[4:5], 1
	v_lshl_add_u64 v[24:25], v[176:177], 0, s[4:5]
	v_lshl_add_u64 v[32:33], v[178:179], 0, s[4:5]
	s_or_b32 s4, s0, 0x2000
	s_mov_b32 s5, s1
	s_lshl_b64 s[4:5], s[4:5], 1
	v_lshl_add_u64 v[40:41], v[176:177], 0, s[4:5]
	v_lshl_add_u64 v[48:49], v[178:179], 0, s[4:5]
	s_or_b32 s4, s0, 0x3000
	s_mov_b32 s5, s1
	s_lshl_b64 s[4:5], s[4:5], 1
	v_lshl_add_u64 v[56:57], v[176:177], 0, s[4:5]
	v_lshl_add_u64 v[64:65], v[178:179], 0, s[4:5]
	s_or_b32 s4, s0, 0x4000
	s_mov_b32 s5, s1
	s_lshl_b64 s[4:5], s[4:5], 1
	v_lshl_add_u64 v[72:73], v[176:177], 0, s[4:5]
	v_lshl_add_u64 v[80:81], v[178:179], 0, s[4:5]
	s_or_b32 s4, s0, 0x5000
	s_mov_b32 s5, s1
	s_lshl_b64 s[4:5], s[4:5], 1
	v_lshl_add_u64 v[88:89], v[176:177], 0, s[4:5]
	v_lshl_add_u64 v[96:97], v[178:179], 0, s[4:5]
	s_or_b32 s4, s0, 0x6000
	s_mov_b32 s5, s1
	s_lshl_b64 s[4:5], s[4:5], 1
	v_lshl_add_u64 v[104:105], v[176:177], 0, s[4:5]
	v_lshl_add_u64 v[108:109], v[178:179], 0, s[4:5]
	s_or_b32 s4, s0, 0x7000
	s_mov_b32 s5, s1
	s_lshl_b64 s[4:5], s[4:5], 1
	v_lshl_add_u64 v[116:117], v[176:177], 0, s[4:5]
	v_lshl_add_u64 v[124:125], v[178:179], 0, s[4:5]
	s_or_b32 s4, s0, 0x8000
	s_mov_b32 s5, s1
	s_lshl_b64 s[4:5], s[4:5], 1
	v_lshl_add_u64 v[132:133], v[176:177], 0, s[4:5]
	v_lshl_add_u64 v[140:141], v[178:179], 0, s[4:5]
	s_or_b32 s4, s0, 0x9000
	s_mov_b32 s5, s1
	s_lshl_b64 s[4:5], s[4:5], 1
	v_lshl_add_u64 v[148:149], v[176:177], 0, s[4:5]
	v_lshl_add_u64 v[156:157], v[178:179], 0, s[4:5]
	s_barrier
	global_load_dwordx4 v[0:3], v[8:9], off
	global_load_dwordx4 v[4:7], v[8:9], off offset:64
	s_nop 0
	global_load_dwordx4 v[8:11], v[16:17], off offset:16
	global_load_dwordx4 v[12:15], v[16:17], off
	s_nop 0
	global_load_dwordx4 v[16:19], v[24:25], off
	global_load_dwordx4 v[20:23], v[24:25], off offset:64
	s_nop 0
	global_load_dwordx4 v[24:27], v[32:33], off offset:16
	global_load_dwordx4 v[28:31], v[32:33], off
	s_nop 0
	global_load_dwordx4 v[32:35], v[40:41], off
	global_load_dwordx4 v[36:39], v[40:41], off offset:64
	s_nop 0
	global_load_dwordx4 v[40:43], v[48:49], off offset:16
	global_load_dwordx4 v[44:47], v[48:49], off
	s_nop 0
	global_load_dwordx4 v[48:51], v[56:57], off
	global_load_dwordx4 v[52:55], v[56:57], off offset:64
	s_nop 0
	global_load_dwordx4 v[56:59], v[64:65], off offset:16
	global_load_dwordx4 v[60:63], v[64:65], off
	s_nop 0
	global_load_dwordx4 v[64:67], v[72:73], off
	global_load_dwordx4 v[68:71], v[72:73], off offset:64
	s_nop 0
	global_load_dwordx4 v[72:75], v[80:81], off offset:16
	global_load_dwordx4 v[76:79], v[80:81], off
	s_nop 0
	global_load_dwordx4 v[80:83], v[88:89], off
	global_load_dwordx4 v[84:87], v[88:89], off offset:64
	s_nop 0
	global_load_dwordx4 v[88:91], v[96:97], off offset:16
	global_load_dwordx4 v[92:95], v[96:97], off
	s_nop 0
	global_load_dwordx4 v[96:99], v[104:105], off
	global_load_dwordx4 v[100:103], v[104:105], off offset:64
	s_nop 0
	global_load_dwordx4 v[104:107], v[108:109], off offset:16
	s_nop 0
	global_load_dwordx4 v[108:111], v[108:109], off
	s_nop 0
	global_load_dwordx4 v[112:115], v[116:117], off
	s_nop 0
	global_load_dwordx4 v[116:119], v[116:117], off offset:64
	s_nop 0
	global_load_dwordx4 v[120:123], v[124:125], off offset:16
	s_nop 0
	global_load_dwordx4 v[124:127], v[124:125], off
	s_nop 0
	global_load_dwordx4 v[128:131], v[132:133], off
	s_nop 0
	global_load_dwordx4 v[132:135], v[132:133], off offset:64
	s_nop 0
	global_load_dwordx4 v[136:139], v[140:141], off offset:16
	s_nop 0
	global_load_dwordx4 v[140:143], v[140:141], off
	s_nop 0
	global_load_dwordx4 v[144:147], v[148:149], off
	s_nop 0
	global_load_dwordx4 v[148:151], v[148:149], off offset:64
	s_nop 0
	global_load_dwordx4 v[152:155], v[156:157], off offset:16
	s_nop 0
	global_load_dwordx4 v[156:159], v[156:157], off
	s_lshl_b32 s6, s2, 7
	s_mov_b64 s[4:5], 0x17348000
	s_mov_b32 s7, s1
	v_lshl_add_u64 v[186:187], s[20:21], 0, v[206:207]
	v_lshl_add_u64 v[186:187], v[186:187], 0, s[4:5]
	s_or_b32 s4, s0, 0x13000
	s_lshl_b32 s10, s2, 20
	s_lshl_b64 s[6:7], s[6:7], 13
	v_and_b32_e32 v184, 15, v185
	v_or_b32_e32 v166, 48, v166
	s_add_u32 s6, s20, s6
	v_mul_u32_u24_e32 v169, 0x48, v184
	v_mul_u32_u24_e32 v166, 0x48, v166
	s_addc_u32 s7, s21, s7
	v_lshl_or_b32 v164, v167, 5, v168
	v_lshlrev_b32_e32 v165, 1, v169
	v_lshlrev_b32_e32 v166, 1, v166
	v_lshl_add_u64 v[188:189], s[6:7], 0, v[206:207]
	v_mov_b32_e32 v162, v161
	v_mov_b32_e32 v163, v161
	v_add_u32_e32 v193, v164, v165
	v_add_u32_e32 v194, v164, v166
	v_add_u32_e32 v195, v165, v160
	v_add_u32_e32 v196, v166, v160
	v_mov_b32_e32 v160, v161
	v_mov_b64_e32 v[174:175], v[162:163]
	v_mov_b64_e32 v[170:171], v[162:163]
	v_mov_b64_e32 v[166:167], v[162:163]
	s_mov_b64 s[6:7], 0
	s_mov_b32 s11, 0x17348000
	s_mov_b32 s12, 0x1734a000
	s_mov_b32 s13, 0x1734c000
	s_mov_b32 s14, 0x1734e000
	s_mov_b32 s15, 0x17350000
	s_mov_b32 s16, 0x17352000
	s_mov_b32 s17, 0x17354000
	s_mov_b32 s29, 0x17356000
	v_mov_b64_e32 v[172:173], v[160:161]
	v_mov_b64_e32 v[168:169], v[160:161]
	v_mov_b64_e32 v[164:165], v[160:161]
	s_mov_b32 s34, 0
	s_branch .LBB0_908

.LBB0_930:
	s_lshl_b32 s0, s2, 14
	s_add_u32 s0, s50, s0
	s_waitcnt vmcnt(17)
	v_lshlrev_b32_e32 v0, 4, v185
	s_movk_i32 s4, 0x300
	s_addc_u32 s1, s51, 0
	v_and_or_b32 v0, v0, s4, v192
	s_add_u32 s0, s0, 0x8112000
	v_or_b32_e32 v2, v0, v184
	s_addc_u32 s1, s1, 0
	v_ashrrev_i32_e32 v3, 31, v2
	v_mov_b32_e32 v185, 0
	v_lshl_add_u64 v[2:3], v[2:3], 2, s[0:1]
	v_ashrrev_i32_e32 v1, 31, v0
	s_waitcnt vmcnt(16)
	v_or_b32_e32 v4, 16, v184
	v_mov_b32_e32 v5, v185
	global_store_dword v[2:3], v164, off
	v_lshl_add_u64 v[2:3], v[0:1], 0, v[184:185]
	v_lshl_add_u64 v[4:5], v[0:1], 0, v[4:5]
	v_lshl_add_u64 v[2:3], v[2:3], 2, s[0:1]
	v_lshl_add_u64 v[4:5], v[4:5], 2, s[0:1]
	global_store_dword v[2:3], v165, off offset:256
	global_store_dword v[2:3], v166, off offset:512
	global_store_dword v[2:3], v167, off offset:768
	global_store_dword v[2:3], v168, off offset:64
	global_store_dword v[4:5], v169, off offset:256
	global_store_dword v[4:5], v170, off offset:512
	global_store_dword v[4:5], v171, off offset:768
	v_or_b32_e32 v4, 32, v184
	v_mov_b32_e32 v5, v185
	v_or_b32_e32 v184, 48, v184
	v_lshl_add_u64 v[4:5], v[0:1], 0, v[4:5]
	v_lshl_add_u64 v[0:1], v[0:1], 0, v[184:185]
	v_lshl_add_u64 v[4:5], v[4:5], 2, s[0:1]
	v_lshl_add_u64 v[0:1], v[0:1], 2, s[0:1]
	global_store_dword v[2:3], v172, off offset:128
	global_store_dword v[4:5], v173, off offset:256
	global_store_dword v[4:5], v174, off offset:512
	global_store_dword v[4:5], v175, off offset:768
	global_store_dword v[2:3], v160, off offset:192
	global_store_dword v[0:1], v161, off offset:256
	global_store_dword v[0:1], v162, off offset:512
	global_store_dword v[0:1], v163, off offset:768
	s_setprio 0
